# e22+e23: first-barrier counter loads issued together, hot loops re-aligned
# baseline (speedup 1.0000x reference)
; __global__ void __launch_bounds__(512, 2) fwd_kernel(Args a) {
;     ...
;                 for (int p = vcu; p < 1024; p += G) { const int hc = p >> 6, pr = p & 63, h = hc & 7, c = hc >> 3;
; #pragma unroll 1
;                     for (int which = 0; which < 2; ++which) { const int qb = which ? pr : 127 - pr;
;                         att::attn_unit2(A0 + (size_t)qb * 128 * D + h * 256 + c * 128, Kb + h * 256 + c * 128, A2 + h * 256,
;                                         A3 + (size_t)c * M * D + (size_t)qb * 128 * D + h * 256, 2 * qb + 2, 2 * qb + ((wave & 3) >> 1), 128 * qb + 32 * (wave & 3), lut + h * 256, ldsg, scr);
;                         __syncthreads(); } } }
.LBB0_424:
	s_add_i32 s48, s48, s49
	s_add_i32 s64, s64, s65
	s_cmpk_gt_i32 s48, 0x3ff
	s_cbranch_scc1 .LBB0_458
	s_nop 0
	s_nop 0
	s_nop 0
	s_nop 0
	s_nop 0
	s_nop 0
	s_nop 0
	s_nop 0
	s_nop 0
	s_nop 0
	s_nop 0
	s_nop 0
	s_nop 0

; template <class Epi, class Sched, bool ALIGN_EPI = false, bool SP2 = false>
; __device__ __forceinline__ void gemm_phase(PG8_LAS unsigned char* lds, const Gemm g, const Sched& S, const Epi& E) {
;     ...
;         const bool has_next = S.next(ui + 1, nxt);
;         const char* nA = has_next ? PG8_UA(nxt) : cA; const char* nB = has_next ? PG8_UB(nxt) : cB;
;         for (int t = 0; t < nt; t += 2) {
;             const bool last = (t == nt - 2);
;             const char* a1 = cA + (size_t)(t + 1) * kstep;
;             const char* a2 = last ? nA : cA + (size_t)(t + 2) * kstep; const char* b2 = last ? nB : cB + (size_t)(t + 2) * kstep;
;             const char* a3 = a2 + kstep; const char* b3 = b2 + kstep;
;     ...
; #pragma unroll
;         for (int a = 0; a < 2; ++a)
; #pragma unroll
;             for (int b = 0; b < 2; ++b)
; #pragma unroll
;                 for (int m = 0; m < 4; ++m)
; #pragma unroll
;                     for (int n = 0; n < 2; ++n) acc[a][b][m][n] = (f32x4){0.f, 0.f, 0.f, 0.f};
.LBB0_1759:
	s_ashr_i32 s53, s52, 31
	s_lshl_b64 s[4:5], s[52:53], 18
	s_add_u32 s64, s18, s4
	s_addc_u32 s65, s19, s5
	s_and_b64 s[4:5], s[42:43], exec
	s_cselect_b32 s4, s65, s67
	s_cselect_b32 s5, s64, s66
	s_add_u32 s42, s62, 0x80080
	s_addc_u32 s43, s63, 0
	s_add_u32 s6, s66, 0x100
	v_mov_b32_e32 v4, 0
	s_addc_u32 s7, s67, 0
	s_mov_b32 s21, -2
	s_waitcnt lgkmcnt(0)
	v_mov_b32_e32 v5, v4
	v_mov_b32_e32 v6, v4
	v_mov_b32_e32 v7, v4
	v_mov_b32_e32 v8, v4
	v_mov_b32_e32 v9, v4
	v_mov_b32_e32 v10, v4
	v_mov_b32_e32 v11, v4
	v_mov_b32_e32 v20, v4
	v_mov_b32_e32 v21, v4
	v_mov_b32_e32 v22, v4
	v_mov_b32_e32 v23, v4
	v_mov_b32_e32 v24, v4
	v_mov_b32_e32 v25, v4
	v_mov_b32_e32 v26, v4
	v_mov_b32_e32 v27, v4
	v_mov_b32_e32 v36, v4
	v_mov_b32_e32 v37, v4
	v_mov_b32_e32 v38, v4
	v_mov_b32_e32 v39, v4
	v_mov_b32_e32 v40, v4
	v_mov_b32_e32 v41, v4
	v_mov_b32_e32 v42, v4
	v_mov_b32_e32 v43, v4
	v_mov_b32_e32 v52, v4
	v_mov_b32_e32 v53, v4
	v_mov_b32_e32 v54, v4
	v_mov_b32_e32 v55, v4
	v_mov_b32_e32 v56, v4
	v_mov_b32_e32 v57, v4
	v_mov_b32_e32 v58, v4
	v_mov_b32_e32 v59, v4
	v_mov_b32_e32 v12, v4
	v_mov_b32_e32 v13, v4
	v_mov_b32_e32 v14, v4
	v_mov_b32_e32 v15, v4
	v_mov_b32_e32 v16, v4
	v_mov_b32_e32 v17, v4
	v_mov_b32_e32 v18, v4
	v_mov_b32_e32 v19, v4
	v_mov_b32_e32 v28, v4
	v_mov_b32_e32 v29, v4
	v_mov_b32_e32 v30, v4
	v_mov_b32_e32 v31, v4
	v_mov_b32_e32 v32, v4
	v_mov_b32_e32 v33, v4
	v_mov_b32_e32 v34, v4
	v_mov_b32_e32 v35, v4
	v_mov_b32_e32 v44, v4
	v_mov_b32_e32 v45, v4
	v_mov_b32_e32 v46, v4
	v_mov_b32_e32 v47, v4
	v_mov_b32_e32 v48, v4
	v_mov_b32_e32 v49, v4
	v_mov_b32_e32 v50, v4
	v_mov_b32_e32 v51, v4
	v_mov_b32_e32 v60, v4
	v_mov_b32_e32 v61, v4
	v_mov_b32_e32 v62, v4
	v_mov_b32_e32 v63, v4
	v_mov_b32_e32 v64, v4
	v_mov_b32_e32 v65, v4
	v_mov_b32_e32 v66, v4
	v_mov_b32_e32 v67, v4
	v_mov_b32_e32 v68, v4
	v_mov_b32_e32 v69, v4
	v_mov_b32_e32 v70, v4
	v_mov_b32_e32 v71, v4
	v_mov_b32_e32 v72, v4
	v_mov_b32_e32 v73, v4
	v_mov_b32_e32 v74, v4
	v_mov_b32_e32 v75, v4
	v_mov_b32_e32 v100, v4
	v_mov_b32_e32 v101, v4
	v_mov_b32_e32 v102, v4
	v_mov_b32_e32 v103, v4
	v_mov_b32_e32 v104, v4
	v_mov_b32_e32 v105, v4
	v_mov_b32_e32 v106, v4
	v_mov_b32_e32 v107, v4
	v_mov_b32_e32 v116, v4
	v_mov_b32_e32 v117, v4
	v_mov_b32_e32 v118, v4
	v_mov_b32_e32 v119, v4
	v_mov_b32_e32 v120, v4
	v_mov_b32_e32 v121, v4
	v_mov_b32_e32 v122, v4
	v_mov_b32_e32 v123, v4
	v_mov_b32_e32 v132, v4
	v_mov_b32_e32 v133, v4
	v_mov_b32_e32 v134, v4
	v_mov_b32_e32 v135, v4
	v_mov_b32_e32 v136, v4
	v_mov_b32_e32 v137, v4
	v_mov_b32_e32 v138, v4
	v_mov_b32_e32 v139, v4
	v_mov_b32_e32 v92, v4
	v_mov_b32_e32 v93, v4
	v_mov_b32_e32 v94, v4
	v_mov_b32_e32 v95, v4
	v_mov_b32_e32 v96, v4
	v_mov_b32_e32 v97, v4
	v_mov_b32_e32 v98, v4
	v_mov_b32_e32 v99, v4
	v_mov_b32_e32 v108, v4
	v_mov_b32_e32 v109, v4
	v_mov_b32_e32 v110, v4
	v_mov_b32_e32 v111, v4
	v_mov_b32_e32 v112, v4
	v_mov_b32_e32 v113, v4
	v_mov_b32_e32 v114, v4
	v_mov_b32_e32 v115, v4
	v_mov_b32_e32 v124, v4
	v_mov_b32_e32 v125, v4
	v_mov_b32_e32 v126, v4
	v_mov_b32_e32 v127, v4
	v_mov_b32_e32 v128, v4
	v_mov_b32_e32 v129, v4
	v_mov_b32_e32 v130, v4
	v_mov_b32_e32 v131, v4
	v_mov_b32_e32 v140, v4
	v_mov_b32_e32 v141, v4
	v_mov_b32_e32 v142, v4
	v_mov_b32_e32 v143, v4
	v_mov_b32_e32 v144, v4
	v_mov_b32_e32 v145, v4
	v_mov_b32_e32 v146, v4
	v_mov_b32_e32 v147, v4
	s_nop 0
	s_nop 0
	s_nop 0
	s_nop 0
